# grid barrier: the acquire invalidate is issued after the arrival atomics (non-leaders before spinning, leaders behind the cross-XCD arrival) instead of before them
# speedup vs baseline: 1.0007x; 1.0007x over previous
.LBB0_47:
	s_or_b64 exec, exec, s[6:7]
	v_cvt_f32_u32_e32 v4, v1
	s_waitcnt vmcnt(0)
	v_readfirstlane_b32 s3, v3
	s_add_i32 s6, 0, 0x22fc8
	v_rcp_iflag_f32_e32 v4, v4
	v_add_u32_e32 v2, s3, v2
	v_mul_f32_e32 v3, 0x4f7ffffe, v4
	v_cvt_u32_f32_e32 v3, v3
	v_sub_u32_e32 v4, 0, v1
	v_mul_lo_u32 v4, v4, v3
	v_mul_hi_u32 v4, v3, v4
	v_add_u32_e32 v3, v3, v4
	v_mul_hi_u32 v3, v2, v3
	v_mul_lo_u32 v4, v3, v1
	v_sub_u32_e32 v4, v2, v4
	v_add_u32_e32 v5, 1, v3
	v_cmp_ge_u32_e32 vcc, v4, v1
	v_add_u32_e32 v2, 1, v2
	s_nop 0
	v_cndmask_b32_e32 v3, v3, v5, vcc
	v_sub_u32_e32 v5, v4, v1
	v_cndmask_b32_e32 v4, v4, v5, vcc
	v_add_u32_e32 v5, 1, v3
	v_cmp_ge_u32_e32 vcc, v4, v1
	v_mov_b32_e32 v4, s6
	s_nop 0
	v_cndmask_b32_e32 v3, v3, v5, vcc
	ds_write_b32 v4, v3
	v_mul_lo_u32 v3, v1, v3
	v_add_u32_e32 v1, v3, v1
	v_cmp_eq_u32_e32 vcc, v2, v1
	s_cbranch_vccnz .Linv_ldr_0
	buffer_inv sc1
.Linv_ldr_0:
	s_and_b64 exec, exec, vcc
	s_cbranch_execz .LBB0_53
	s_mov_b64 s[6:7], exec
	buffer_wbl2 sc1
	s_waitcnt lgkmcnt(0)
	s_waitcnt vmcnt(0)
	v_mbcnt_lo_u32_b32 v1, s6, 0
	v_mbcnt_hi_u32_b32 v1, s7, v1
	v_cmp_eq_u32_e32 vcc, 0, v1
	s_and_saveexec_b64 s[8:9], vcc
	s_cbranch_execz .LBB0_50
	s_bcnt1_i32_b64 s3, s[6:7]
	v_mov_b32_e32 v2, 0x17000
	v_mov_b32_e32 v3, s3
	global_atomic_add v2, v2, v3, s[68:69] offset:1024 sc0
	buffer_inv sc1

.LBB0_109:
	s_or_b64 exec, exec, s[4:5]
	v_cvt_f32_u32_e32 v4, v1
	s_waitcnt vmcnt(0)
	v_readfirstlane_b32 s3, v3
	s_add_i32 s4, 0, 0x22fc8
	v_rcp_iflag_f32_e32 v4, v4
	v_add_u32_e32 v2, s3, v2
	v_mul_f32_e32 v3, 0x4f7ffffe, v4
	v_cvt_u32_f32_e32 v3, v3
	v_sub_u32_e32 v4, 0, v1
	v_mul_lo_u32 v4, v4, v3
	v_mul_hi_u32 v4, v3, v4
	v_add_u32_e32 v3, v3, v4
	v_mul_hi_u32 v3, v2, v3
	v_mul_lo_u32 v4, v3, v1
	v_sub_u32_e32 v4, v2, v4
	v_add_u32_e32 v5, 1, v3
	v_cmp_ge_u32_e32 vcc, v4, v1
	v_add_u32_e32 v2, 1, v2
	s_nop 0
	v_cndmask_b32_e32 v3, v3, v5, vcc
	v_sub_u32_e32 v5, v4, v1
	v_cndmask_b32_e32 v4, v4, v5, vcc
	v_add_u32_e32 v5, 1, v3
	v_cmp_ge_u32_e32 vcc, v4, v1
	v_mov_b32_e32 v4, s4
	s_nop 0
	v_cndmask_b32_e32 v3, v3, v5, vcc
	ds_write_b32 v4, v3
	v_mul_lo_u32 v3, v1, v3
	v_add_u32_e32 v1, v3, v1
	v_cmp_eq_u32_e32 vcc, v2, v1
	s_cbranch_vccnz .Linv_ldr_1
	buffer_inv sc1
.Linv_ldr_1:
	s_and_b64 exec, exec, vcc
	s_cbranch_execz .LBB0_115
	s_mov_b64 s[4:5], exec
	buffer_wbl2 sc1
	s_waitcnt lgkmcnt(0)
	s_waitcnt vmcnt(0)
	v_mbcnt_lo_u32_b32 v1, s4, 0
	v_mbcnt_hi_u32_b32 v1, s5, v1
	v_cmp_eq_u32_e32 vcc, 0, v1
	s_and_saveexec_b64 s[6:7], vcc
	s_cbranch_execz .LBB0_112
	s_bcnt1_i32_b64 s3, s[4:5]
	v_mov_b32_e32 v2, 0x17000
	v_mov_b32_e32 v3, s3
	global_atomic_add v2, v2, v3, s[68:69] offset:1024 sc0
	buffer_inv sc1

.LBB0_900:
	s_or_b64 exec, exec, s[6:7]
	v_cvt_f32_u32_e32 v4, v1
	s_waitcnt vmcnt(0)
	v_readfirstlane_b32 s2, v3
	s_add_i32 s3, 0, 0x22fc8
	v_rcp_iflag_f32_e32 v4, v4
	v_add_u32_e32 v2, s2, v2
	v_mul_f32_e32 v3, 0x4f7ffffe, v4
	v_cvt_u32_f32_e32 v3, v3
	v_sub_u32_e32 v4, 0, v1
	v_mul_lo_u32 v4, v4, v3
	v_mul_hi_u32 v4, v3, v4
	v_add_u32_e32 v3, v3, v4
	v_mul_hi_u32 v3, v2, v3
	v_mul_lo_u32 v4, v3, v1
	v_sub_u32_e32 v4, v2, v4
	v_add_u32_e32 v5, 1, v3
	v_cmp_ge_u32_e32 vcc, v4, v1
	v_add_u32_e32 v2, 1, v2
	s_nop 0
	v_cndmask_b32_e32 v3, v3, v5, vcc
	v_sub_u32_e32 v5, v4, v1
	v_cndmask_b32_e32 v4, v4, v5, vcc
	v_add_u32_e32 v5, 1, v3
	v_cmp_ge_u32_e32 vcc, v4, v1
	v_mov_b32_e32 v4, s3
	s_nop 0
	v_cndmask_b32_e32 v3, v3, v5, vcc
	ds_write_b32 v4, v3
	v_mul_lo_u32 v3, v1, v3
	v_add_u32_e32 v1, v3, v1
	v_cmp_eq_u32_e32 vcc, v2, v1
	s_cbranch_vccnz .Linv_ldr_5
	buffer_inv sc1
.Linv_ldr_5:
	s_and_b64 exec, exec, vcc
	s_cbranch_execz .LBB0_906
	s_mov_b64 s[6:7], exec
	buffer_wbl2 sc1
	s_waitcnt lgkmcnt(0)
	s_waitcnt vmcnt(0)
	v_mbcnt_lo_u32_b32 v1, s6, 0
	v_mbcnt_hi_u32_b32 v1, s7, v1
	v_cmp_eq_u32_e32 vcc, 0, v1
	s_and_saveexec_b64 s[8:9], vcc
	s_cbranch_execz .LBB0_903
	s_bcnt1_i32_b64 s2, s[6:7]
	v_mov_b32_e32 v2, 0x17000
	v_mov_b32_e32 v3, s2
	global_atomic_add v2, v2, v3, s[68:69] offset:1024 sc0
	buffer_inv sc1

.LBB0_991:
	s_or_b64 exec, exec, s[4:5]
	v_cvt_f32_u32_e32 v4, v1
	s_waitcnt vmcnt(0)
	v_readfirstlane_b32 s2, v3
	s_add_i32 s3, 0, 0x22fc8
	v_rcp_iflag_f32_e32 v4, v4
	v_add_u32_e32 v2, s2, v2
	v_mul_f32_e32 v3, 0x4f7ffffe, v4
	v_cvt_u32_f32_e32 v3, v3
	v_sub_u32_e32 v4, 0, v1
	v_mul_lo_u32 v4, v4, v3
	v_mul_hi_u32 v4, v3, v4
	v_add_u32_e32 v3, v3, v4
	v_mul_hi_u32 v3, v2, v3
	v_mul_lo_u32 v4, v3, v1
	v_sub_u32_e32 v4, v2, v4
	v_add_u32_e32 v5, 1, v3
	v_cmp_ge_u32_e32 vcc, v4, v1
	v_add_u32_e32 v2, 1, v2
	s_nop 0
	v_cndmask_b32_e32 v3, v3, v5, vcc
	v_sub_u32_e32 v5, v4, v1
	v_cndmask_b32_e32 v4, v4, v5, vcc
	v_add_u32_e32 v5, 1, v3
	v_cmp_ge_u32_e32 vcc, v4, v1
	v_mov_b32_e32 v4, s3
	s_nop 0
	v_cndmask_b32_e32 v3, v3, v5, vcc
	ds_write_b32 v4, v3
	v_mul_lo_u32 v3, v1, v3
	v_add_u32_e32 v1, v3, v1
	v_cmp_eq_u32_e32 vcc, v2, v1
	s_cbranch_vccnz .Linv_ldr_6
	buffer_inv sc1
.Linv_ldr_6:
	s_and_b64 exec, exec, vcc
	s_cbranch_execz .LBB0_997
	s_mov_b64 s[4:5], exec
	buffer_wbl2 sc1
	s_waitcnt lgkmcnt(0)
	s_waitcnt vmcnt(0)
	v_mbcnt_lo_u32_b32 v1, s4, 0
	v_mbcnt_hi_u32_b32 v1, s5, v1
	v_cmp_eq_u32_e32 vcc, 0, v1
	s_and_saveexec_b64 s[8:9], vcc
	s_cbranch_execz .LBB0_994
	s_bcnt1_i32_b64 s2, s[4:5]
	v_mov_b32_e32 v2, 0x17000
	v_mov_b32_e32 v3, s2
	global_atomic_add v2, v2, v3, s[68:69] offset:1024 sc0
	buffer_inv sc1

.LBB0_1079:
	s_or_b64 exec, exec, s[10:11]
	v_cvt_f32_u32_e32 v4, v2
	s_waitcnt vmcnt(0)
	v_readfirstlane_b32 s2, v3
	v_sub_u32_e32 v3, 0, v2
	v_rcp_iflag_f32_e32 v4, v4
	v_add_u32_e32 v5, s2, v1
	v_mul_f32_e32 v4, 0x4f7ffffe, v4
	v_cvt_u32_f32_e32 v4, v4
	v_mul_lo_u32 v1, v3, v4
	v_mul_hi_u32 v1, v4, v1
	v_add_u32_e32 v1, v4, v1
	v_mul_hi_u32 v1, v5, v1
	v_mul_lo_u32 v3, v1, v2
	v_sub_u32_e32 v3, v5, v3
	v_add_u32_e32 v4, 1, v1
	v_cmp_ge_u32_e32 vcc, v3, v2
	s_nop 1
	v_cndmask_b32_e32 v1, v1, v4, vcc
	v_sub_u32_e32 v4, v3, v2
	v_cndmask_b32_e32 v3, v3, v4, vcc
	v_add_u32_e32 v4, 1, v1
	v_cmp_ge_u32_e32 vcc, v3, v2
	v_add_u32_e32 v3, 1, v5
	s_nop 0
	v_cndmask_b32_e32 v1, v1, v4, vcc
	v_mul_lo_u32 v4, v2, v1
	v_add_u32_e32 v2, v4, v2
	v_cmp_ne_u32_e32 vcc, v3, v2
	s_and_saveexec_b64 s[2:3], vcc
	s_xor_b64 s[10:11], exec, s[2:3]
	s_cbranch_execz .LBB0_1093
	buffer_inv sc1
	s_waitcnt lgkmcnt(0)
	v_add_u32_e32 v1, 1, v1
	v_mul_lo_u32 v1, v1, v0
	v_mov_b32_e32 v0, 0x17000
	global_load_dword v0, v0, s[68:69] offset:1024 sc1
	s_add_u32 s18, s68, 0x17500
	s_addc_u32 s19, s69, 0
	s_waitcnt vmcnt(0)
	v_cmp_lt_u32_e32 vcc, v0, v1
	s_and_saveexec_b64 s[12:13], vcc
	s_cbranch_execz .LBB0_1092
	s_add_u32 s16, s68, 0x14200
	s_addc_u32 s17, s69, 0
	s_mov_b32 s2, 1
	s_mov_b64 s[20:21], 0
	v_mov_b32_e32 v0, 0
	s_branch .LBB0_1083

.LBB0_1093:
	s_andn2_saveexec_b64 s[2:3], s[10:11]
	s_cbranch_execz .LBB0_1111
	s_mov_b64 s[10:11], exec
	buffer_wbl2 sc1
	s_waitcnt lgkmcnt(0)
	s_waitcnt vmcnt(0)
	v_mbcnt_lo_u32_b32 v1, s10, 0
	v_mbcnt_hi_u32_b32 v1, s11, v1
	v_cmp_eq_u32_e32 vcc, 0, v1
	s_and_saveexec_b64 s[12:13], vcc
	s_cbranch_execz .LBB0_1096
	s_bcnt1_i32_b64 s2, s[10:11]
	v_mov_b32_e32 v2, 0x17000
	v_mov_b32_e32 v3, s2
	global_atomic_add v2, v2, v3, s[68:69] offset:1024 sc0
	buffer_inv sc1

.LBB0_1148:
	s_or_b64 exec, exec, s[8:9]
	v_cvt_f32_u32_e32 v4, v2
	s_waitcnt vmcnt(0)
	v_readfirstlane_b32 s2, v3
	v_sub_u32_e32 v3, 0, v2
	v_rcp_iflag_f32_e32 v4, v4
	v_add_u32_e32 v5, s2, v1
	v_mul_f32_e32 v4, 0x4f7ffffe, v4
	v_cvt_u32_f32_e32 v4, v4
	v_mul_lo_u32 v1, v3, v4
	v_mul_hi_u32 v1, v4, v1
	v_add_u32_e32 v1, v4, v1
	v_mul_hi_u32 v1, v5, v1
	v_mul_lo_u32 v3, v1, v2
	v_sub_u32_e32 v3, v5, v3
	v_add_u32_e32 v4, 1, v1
	v_cmp_ge_u32_e32 vcc, v3, v2
	s_nop 1
	v_cndmask_b32_e32 v1, v1, v4, vcc
	v_sub_u32_e32 v4, v3, v2
	v_cndmask_b32_e32 v3, v3, v4, vcc
	v_add_u32_e32 v4, 1, v1
	v_cmp_ge_u32_e32 vcc, v3, v2
	v_add_u32_e32 v3, 1, v5
	s_nop 0
	v_cndmask_b32_e32 v1, v1, v4, vcc
	v_mul_lo_u32 v4, v2, v1
	v_add_u32_e32 v2, v4, v2
	v_cmp_ne_u32_e32 vcc, v3, v2
	s_and_saveexec_b64 s[2:3], vcc
	s_xor_b64 s[8:9], exec, s[2:3]
	s_cbranch_execz .LBB0_1162
	buffer_inv sc1
	s_waitcnt lgkmcnt(0)
	v_add_u32_e32 v1, 1, v1
	v_mul_lo_u32 v1, v1, v0
	v_mov_b32_e32 v0, 0x17000
	global_load_dword v0, v0, s[68:69] offset:1024 sc1
	s_add_u32 s14, s68, 0x17500
	s_addc_u32 s15, s69, 0
	s_waitcnt vmcnt(0)
	v_cmp_lt_u32_e32 vcc, v0, v1
	s_and_saveexec_b64 s[10:11], vcc
	s_cbranch_execz .LBB0_1161
	s_add_u32 s12, s68, 0x14200
	s_addc_u32 s13, s69, 0
	s_mov_b32 s2, 1
	s_mov_b64 s[16:17], 0
	v_mov_b32_e32 v0, 0
	s_branch .LBB0_1152

.LBB0_1162:
	s_andn2_saveexec_b64 s[2:3], s[8:9]
	s_cbranch_execz .LBB0_1180
	s_mov_b64 s[8:9], exec
	buffer_wbl2 sc1
	s_waitcnt lgkmcnt(0)
	s_waitcnt vmcnt(0)
	v_mbcnt_lo_u32_b32 v1, s8, 0
	v_mbcnt_hi_u32_b32 v1, s9, v1
	v_cmp_eq_u32_e32 vcc, 0, v1
	s_and_saveexec_b64 s[10:11], vcc
	s_cbranch_execz .LBB0_1165
	s_bcnt1_i32_b64 s2, s[8:9]
	v_mov_b32_e32 v2, 0x17000
	v_mov_b32_e32 v3, s2
	global_atomic_add v2, v2, v3, s[68:69] offset:1024 sc0
	buffer_inv sc1
